# SSD and mLSTM chunk-prefetch address computation replaced by saved-base plus scalar offset fast path; GLA gate dot uses packed fma with read2 pairs
# speedup vs baseline: 1.0039x; 1.0039x over previous
.LBB0_413:
	s_or_b64 exec, exec, s[76:77]
	s_cmpk_gt_u32 s29, 0x81
	s_cbranch_scc1 .LBB0_415
	s_cmp_gt_u32 s29, 3
	s_cbranch_scc0 .Lml_issue_slow
	s_add_i32 s36, s29, -3
	s_mul_i32 s37, s36, 0x68000
	s_mul_i32 s36, s36, 0x6000
	s_cmp_lg_u64 s[40:41], 0
	s_cbranch_scc1 .Lml_issue_pos
	s_sub_i32 s37, 0, s37
	s_sub_i32 s36, 0, s36
.Lml_issue_pos:
	s_mov_b32 s76, s37
	s_ashr_i32 s77, s37, 31
	v_lshl_add_u64 v[0:1], v[210:211], 0, s[76:77]
	v_lshl_add_u64 v[4:5], v[212:213], 0, s[76:77]
	v_lshl_add_u64 v[8:9], v[214:215], 0, s[76:77]
	v_lshl_add_u64 v[12:13], v[216:217], 0, s[76:77]
	s_mov_b32 s76, s36
	s_ashr_i32 s77, s36, 31
	v_lshl_add_u64 v[208:209], v[218:219], 0, s[76:77]
	global_load_dwordx4 v[0:3], v[0:1], off offset:3664
	global_load_dwordx4 v[4:7], v[4:5], off offset:3664
	global_load_dwordx4 v[8:11], v[8:9], off offset:3664
	global_load_dwordx4 v[12:15], v[12:13], off offset:592
	global_load_dword v82, v[208:209], off offset:256
	global_load_dword v83, v[208:209], off offset:272
	s_branch .LBB0_415
.Lml_issue_slow:
	s_cmp_lt_u32 s29, 2
	s_cselect_b32 s36, 2, -2
	s_cselect_b32 s38, s23, 0x2000
	s_cselect_b32 s39, s16, s28
	s_add_i32 s36, s36, s29
	s_lshl_b32 s76, s36, 6
	s_add_i32 s77, s38, -1
	v_add_u32_e32 v0, s76, v69
	v_add_u32_e32 v10, s76, v71
	v_min_i32_e32 v1, s77, v0
	v_cmp_lt_i32_e32 vcc, -1, v0
	v_add_u32_e32 v2, s76, v70
	v_xad_u32 v11, v10, -1, s38
	v_cndmask_b32_e32 v0, 0, v1, vcc
	v_min_i32_e32 v3, s77, v2
	v_cmp_lt_i32_e32 vcc, -1, v2
	v_add_u32_e32 v8, s76, v78
	v_cndmask_b32_e64 v10, v11, v10, s[40:41]
	v_cndmask_b32_e32 v2, 0, v3, vcc
	v_min_i32_e32 v9, s77, v8
	v_cmp_lt_i32_e32 vcc, -1, v8
	v_add_u32_e32 v12, s39, v10
	v_mov_b64_e32 v[10:11], s[12:13]
	v_cndmask_b32_e32 v8, 0, v9, vcc
	v_mad_i64_i32 v[10:11], s[36:37], v12, s20, v[10:11]
	s_waitcnt lgkmcnt(11)
	v_or_b32_e32 v40, s76, v62
	v_xad_u32 v1, v0, -1, s38
	v_xad_u32 v3, v2, -1, s38
	v_xad_u32 v9, v8, -1, s38
	v_lshl_add_u64 v[10:11], v[10:11], 0, s[84:85]
	s_waitcnt lgkmcnt(10)
	v_xad_u32 v41, v40, -1, s38
	v_cndmask_b32_e64 v0, v1, v0, s[40:41]
	v_cndmask_b32_e64 v2, v3, v2, s[40:41]
	v_cndmask_b32_e64 v8, v9, v8, s[40:41]
	v_lshl_add_u64 v[10:11], v[10:11], 0, v[168:169]
	v_cndmask_b32_e64 v40, v41, v40, s[40:41]
	v_add_u32_e32 v0, s39, v0
	v_add_u32_e32 v2, s39, v2
	v_add_u32_e32 v8, s39, v8
	v_add_co_u32_e32 v12, vcc, 0x1000, v10
	v_add_u32_e32 v42, s39, v40
	v_mov_b64_e32 v[40:41], s[8:9]
	v_mad_i64_i32 v[0:1], s[36:37], v0, s20, v[56:57]
	v_mad_i64_i32 v[4:5], s[36:37], v2, s20, v[56:57]
	v_mad_i64_i32 v[8:9], s[36:37], v8, s20, v[56:57]
	v_addc_co_u32_e32 v13, vcc, 0, v11, vcc
	v_mad_i64_i32 v[40:41], s[36:37], v42, s21, v[40:41]
	v_mov_b64_e32 v[210:211], v[0:1]
	global_load_dwordx4 v[0:3], v[0:1], off offset:3664
	s_nop 0
	v_mov_b64_e32 v[212:213], v[4:5]
	global_load_dwordx4 v[4:7], v[4:5], off offset:3664
	s_nop 0
	v_mov_b64_e32 v[214:215], v[8:9]
	global_load_dwordx4 v[8:11], v[8:9], off offset:3664
	s_nop 0
	v_mov_b64_e32 v[216:217], v[12:13]
	global_load_dwordx4 v[12:15], v[12:13], off offset:592
	s_nop 0
	v_mov_b64_e32 v[218:219], v[40:41]
	global_load_dword v82, v[40:41], off offset:256
	global_load_dword v83, v[40:41], off offset:272

.LBB0_449:
	s_cmp_gt_u32 s35, 3
	s_cbranch_scc0 .Lssd_issue_slow
	s_add_i32 s16, s35, -2
	s_and_b32 s17, s16, 1
	s_lshl_b32 s17, s17, 12
	s_lshr_b32 s36, s16, 1
	s_add_i32 s17, s17, s36
	s_add_i32 s36, s16, -1
	s_and_b32 s37, s36, 1
	s_lshl_b32 s37, s37, 12
	s_lshr_b32 s36, s36, 1
	s_add_i32 s36, s36, s37
	s_add_i32 s37, s16, 1
	s_and_b32 s74, s37, 1
	s_lshl_b32 s74, s74, 12
	s_lshr_b32 s37, s37, 1
	s_add_i32 s37, s37, s74
	s_add_i32 s37, s37, -1
	s_add_i32 s17, s17, 0xfffff000
	s_mul_i32 s78, s17, 0x1a00
	s_mul_i32 s79, s17, 0x180
	s_mul_i32 s36, s36, 0x1a00
	s_mul_i32 s37, s37, 0x1a00
	s_cmp_lg_u64 s[40:41], 0
	s_cbranch_scc1 .Lssd_issue_pos
	s_sub_i32 s78, 0, s78
	s_sub_i32 s79, 0, s79
	s_sub_i32 s36, 0, s36
	s_sub_i32 s37, 0, s37
.Lssd_issue_pos:
	s_mov_b32 s16, s78
	s_ashr_i32 s17, s78, 31
	v_cmp_gt_i32_e32 vcc, 0, v81
	v_lshl_add_u64 v[0:1], v[210:211], 0, s[16:17]
	v_lshl_add_u64 v[4:5], v[212:213], 0, s[16:17]
	v_lshl_add_u64 v[8:9], v[214:215], 0, s[16:17]
	global_load_dwordx4 v[0:3], v[0:1], off
	global_load_dwordx4 v[4:7], v[4:5], off
	global_load_dwordx4 v[8:11], v[8:9], off
	v_mov_b32_e32 v12, s37
	v_mov_b32_e32 v13, s36
	s_mov_b32 s16, s79
	s_ashr_i32 s17, s79, 31
	v_cndmask_b32_e32 v12, v12, v13, vcc
	v_lshl_add_u64 v[112:113], v[218:219], 0, s[16:17]
	v_ashrrev_i32_e32 v13, 31, v12
	v_lshl_add_u64 v[12:13], v[216:217], 0, v[12:13]
	global_load_dwordx4 v[12:15], v[12:13], off
	global_load_dword v88, v[112:113], off offset:128
	s_branch .LBB0_470

.LBB0_453:
	v_mad_i64_i32 v[0:1], s[16:17], v1, s20, v[50:51]
	v_mov_b64_e32 v[210:211], v[0:1]
	global_load_dwordx4 v[0:3], v[0:1], off
	v_add_u32_e32 v4, s37, v69
	v_min_i32_e32 v5, s38, v4
	v_cmp_lt_i32_e32 vcc, -1, v4
	s_mov_b64 s[16:17], -1
	s_nop 0
	v_cndmask_b32_e32 v4, 0, v5, vcc
	v_xad_u32 v5, v4, -1, s36
	v_cndmask_b32_e64 v4, v5, v4, s[40:41]
	v_cndmask_b32_e64 v5, 0, 1, s[78:79]
	v_cmp_ne_u32_e64 s[74:75], 1, v5
	s_andn2_b64 vcc, exec, s[78:79]
	s_cbranch_vccnz .LBB0_455
	v_lshlrev_b32_e32 v5, 6, v4
	v_and_b32_e32 v5, 0x1fc0, v5
	v_ashrrev_i32_e32 v6, 7, v4
	v_add3_u32 v5, v6, s30, v5
	s_mov_b64 s[16:17], 0

.LBB0_457:
	v_mad_i64_i32 v[4:5], s[16:17], v5, s20, v[52:53]
	v_mov_b64_e32 v[212:213], v[4:5]
	global_load_dwordx4 v[4:7], v[4:5], off
	v_add_u32_e32 v8, s37, v70
	v_min_i32_e32 v9, s38, v8
	v_cmp_lt_i32_e32 vcc, -1, v8
	s_mov_b64 s[16:17], -1
	s_nop 0
	v_cndmask_b32_e32 v8, 0, v9, vcc
	v_xad_u32 v9, v8, -1, s36
	v_cndmask_b32_e64 v8, v9, v8, s[40:41]
	s_and_b64 vcc, exec, s[74:75]
	s_cbranch_vccnz .LBB0_459
	v_lshlrev_b32_e32 v9, 6, v8
	v_and_b32_e32 v9, 0x1fc0, v9
	v_ashrrev_i32_e32 v10, 7, v8
	v_add3_u32 v9, v10, s30, v9
	s_mov_b64 s[16:17], 0

.LBB0_461:
	v_mad_i64_i32 v[8:9], s[16:17], v9, s20, v[54:55]
	v_mov_b64_e32 v[214:215], v[8:9]
	global_load_dwordx4 v[8:11], v[8:9], off
	s_waitcnt vmcnt(4)
	v_add_u32_e32 v12, s37, v81
	v_min_i32_e32 v13, s38, v12
	v_cmp_lt_i32_e32 vcc, -1, v12
	s_mov_b64 s[74:75], -1
	s_nop 0
	v_cndmask_b32_e32 v12, 0, v13, vcc
	v_xad_u32 v13, v12, -1, s36
	v_cndmask_b32_e64 v12, v13, v12, s[40:41]
	s_and_b64 vcc, exec, s[78:79]
	s_cbranch_vccz .LBB0_463
	v_lshlrev_b32_e32 v13, 6, v12
	v_and_b32_e32 v13, 0x1fc0, v13
	v_ashrrev_i32_e32 v14, 7, v12
	v_add3_u32 v13, v14, s30, v13
	s_mov_b64 s[74:75], 0

.LBB0_465:
	v_mad_i64_i32 v[12:13], s[16:17], v13, s20, v[56:57]
	v_mov_b64_e32 v[216:217], v[12:13]
	global_load_dwordx4 v[12:15], v[12:13], off
	v_or_b32_e32 v60, s37, v62
	s_waitcnt vmcnt(4)
	v_xad_u32 v88, v60, -1, s36
	v_cndmask_b32_e64 v60, v88, v60, s[40:41]
	s_mov_b64 s[74:75], -1
	s_and_b64 vcc, exec, s[78:79]
	s_cbranch_vccz .LBB0_467
	v_lshlrev_b32_e32 v88, 6, v60
	v_and_b32_e32 v88, 0x1fc0, v88
	v_ashrrev_i32_e32 v111, 7, v60
	v_add3_u32 v88, v111, s30, v88
	s_mov_b64 s[74:75], 0

.LBB0_469:
	v_mov_b64_e32 v[112:113], s[76:77]
	v_mad_i64_i32 v[112:113], s[16:17], v88, s21, v[112:113]
	v_mov_b64_e32 v[218:219], v[112:113]
	global_load_dword v88, v[112:113], off offset:128

.LBB0_494:
	s_add_i32 s37, s16, 0xffffff00
	s_cmp_lt_u32 s29, 4
	s_mul_i32 s36, s35, 0x13a00
	s_mul_i32 s8, s35, 0x10200
	s_mul_i32 s9, s35, 0xa200
	s_cselect_b32 s35, s16, s37
	v_add_u32_e32 v75, s35, v64
	s_cselect_b32 s35, 0xff, s22
	v_sub_u32_e32 v76, s35, v75
	v_cndmask_b32_e32 v75, v76, v75, vcc
	s_cselect_b32 s35, s28, s17
	v_add_u32_e32 v76, s35, v75
	v_add_u32_e32 v90, s36, v66
	v_ashrrev_i32_e32 v77, 31, v76
	v_add_u32_e32 v75, v90, v71
	s_waitcnt lgkmcnt(0)
	s_barrier
	ds_read_b128 v[132:135], v65 offset:55296
	ds_read_b128 v[136:139], v65 offset:55360
	ds_read_b128 v[140:143], v75 offset:18432
	ds_read_b128 v[144:147], v75 offset:18496
	v_add_u32_e32 v129, v90, v72
	ds_read_b128 v[148:151], v129 offset:18432
	ds_read_b128 v[152:155], v129 offset:18496
	v_add_u32_e32 v131, s34, v59
	ds_read2_b32 v[172:173], v131 offset0:0 offset1:4
	ds_read2_b32 v[174:175], v131 offset0:1 offset1:5
	ds_read2_b32 v[176:177], v131 offset0:2 offset1:6
	ds_read2_b32 v[178:179], v131 offset0:3 offset1:7
	ds_read2_b32 v[180:181], v131 offset0:8 offset1:12
	ds_read2_b32 v[182:183], v131 offset0:9 offset1:13
	ds_read2_b32 v[184:185], v131 offset0:10 offset1:14
	ds_read2_b32 v[186:187], v131 offset0:11 offset1:15
	ds_read2_b32 v[188:189], v131 offset0:16 offset1:20
	ds_read2_b32 v[190:191], v131 offset0:17 offset1:21
	ds_read2_b32 v[192:193], v131 offset0:18 offset1:22
	ds_read2_b32 v[194:195], v131 offset0:19 offset1:23
	ds_read2_b32 v[196:197], v131 offset0:24 offset1:28
	ds_read2_b32 v[198:199], v131 offset0:25 offset1:29
	ds_read2_b32 v[200:201], v131 offset0:26 offset1:30
	ds_read2_b32 v[202:203], v131 offset0:27 offset1:31
	ds_read2_b32 v[204:205], v131 offset0:32 offset1:36
	ds_read2_b32 v[206:207], v131 offset0:33 offset1:37
	ds_read2_b32 v[208:209], v131 offset0:34 offset1:38
	ds_read2_b32 v[210:211], v131 offset0:35 offset1:39
	ds_read2_b32 v[212:213], v131 offset0:40 offset1:44
	ds_read2_b32 v[214:215], v131 offset0:41 offset1:45
	ds_read2_b32 v[216:217], v131 offset0:42 offset1:46
	ds_read2_b32 v[218:219], v131 offset0:43 offset1:47
	v_lshlrev_b64 v[88:89], 11, v[76:77]
	s_nop 0
	s_nop 0
	s_waitcnt lgkmcnt(12)
	v_mfma_f32_16x16x32_bf16 v[28:31], v[140:143], v[132:135], v[28:31]
	s_nop 0
	v_mfma_f32_16x16x32_bf16 v[28:31], v[144:147], v[136:139], v[28:31]
	s_nop 7
	v_cvt_pk_bf16_f32 v28, v28, v29
	v_cvt_pk_bf16_f32 v29, v30, v31
	v_lshl_add_u64 v[30:31], v[52:53], 0, v[88:89]
	global_store_dwordx2 v[30:31], v[28:29], off
	v_add_u32_e32 v28, v90, v72
	s_nop 0
	v_mfma_f32_16x16x32_bf16 v[24:27], v[148:151], v[132:135], v[24:27]
	s_nop 0
	v_mfma_f32_16x16x32_bf16 v[24:27], v[152:155], v[136:139], v[24:27]
	s_nop 7
	v_cvt_pk_bf16_f32 v24, v24, v25
	v_cvt_pk_bf16_f32 v25, v26, v27
	global_store_dwordx2 v[30:31], v[24:25], off offset:32
	v_pk_mul_f32 v[156:157], v[34:35], v[174:175]
	v_pk_mul_f32 v[158:159], v[42:43], v[182:183]
	v_pk_fma_f32 v[156:157], v[32:33], v[172:173], v[156:157]
	v_pk_fma_f32 v[158:159], v[40:41], v[180:181], v[158:159]
	v_pk_fma_f32 v[156:157], v[36:37], v[176:177], v[156:157]
	v_pk_fma_f32 v[158:159], v[44:45], v[184:185], v[158:159]
	v_pk_fma_f32 v[156:157], v[38:39], v[178:179], v[156:157]
	v_pk_fma_f32 v[158:159], v[46:47], v[186:187], v[158:159]
	ds_read2_b32 v[172:173], v131 offset0:48 offset1:52
	ds_read2_b32 v[174:175], v131 offset0:49 offset1:53
	ds_read2_b32 v[176:177], v131 offset0:50 offset1:54
	ds_read2_b32 v[178:179], v131 offset0:51 offset1:55
	ds_read2_b32 v[180:181], v131 offset0:56 offset1:60
	ds_read2_b32 v[182:183], v131 offset0:57 offset1:61
	ds_read2_b32 v[184:185], v131 offset0:58 offset1:62
	ds_read2_b32 v[186:187], v131 offset0:59 offset1:63
	v_add_f32_e32 v164, v54, v156
	v_pk_mul_f32 v[160:161], v[34:35], v[190:191]
	s_waitcnt lgkmcnt(12)
	v_pk_mul_f32 v[162:163], v[42:43], v[198:199]
	v_add_f32_e32 v164, v164, v157
	v_pk_fma_f32 v[160:161], v[32:33], v[188:189], v[160:161]
	v_pk_fma_f32 v[162:163], v[40:41], v[196:197], v[162:163]
	v_add_f32_e32 v164, v164, v158
	v_pk_fma_f32 v[160:161], v[36:37], v[192:193], v[160:161]
	v_pk_fma_f32 v[162:163], v[44:45], v[200:201], v[162:163]
	v_add_f32_e32 v164, v164, v159
	v_pk_fma_f32 v[160:161], v[38:39], v[194:195], v[160:161]
	v_min_f32_e32 v166, 0, v164
	v_pk_fma_f32 v[162:163], v[46:47], v[202:203], v[162:163]
	v_mul_f32_e64 v164, |v164|, s19
	ds_read2_b32 v[188:189], v131 offset0:64 offset1:68
	v_exp_f32_e32 v164, v164
	ds_read2_b32 v[190:191], v131 offset0:65 offset1:69
	ds_read2_b32 v[192:193], v131 offset0:66 offset1:70
	v_add_f32_e32 v164, 1.0, v164
	ds_read2_b32 v[194:195], v131 offset0:67 offset1:71
	v_log_f32_e32 v164, v164
	ds_read2_b32 v[196:197], v131 offset0:72 offset1:76
	ds_read2_b32 v[198:199], v131 offset0:73 offset1:77
	v_fmac_f32_e32 v166, 0xbf317218, v164
	ds_read2_b32 v[200:201], v131 offset0:74 offset1:78
	v_fma_f32 v25, v166, s26, 0
	ds_read2_b32 v[202:203], v131 offset0:75 offset1:79
	v_add_f32_e32 v165, v54, v160
	v_pk_mul_f32 v[156:157], v[34:35], v[206:207]
	s_waitcnt lgkmcnt(12)
	v_pk_mul_f32 v[158:159], v[42:43], v[214:215]
	v_add_f32_e32 v165, v165, v161
	v_pk_fma_f32 v[156:157], v[32:33], v[204:205], v[156:157]
	v_pk_fma_f32 v[158:159], v[40:41], v[212:213], v[158:159]
	v_add_f32_e32 v165, v165, v162
	v_pk_fma_f32 v[156:157], v[36:37], v[208:209], v[156:157]
	v_pk_fma_f32 v[158:159], v[44:45], v[216:217], v[158:159]
	v_add_f32_e32 v165, v165, v163
	v_pk_fma_f32 v[156:157], v[38:39], v[210:211], v[156:157]
	v_min_f32_e32 v167, 0, v165
	v_pk_fma_f32 v[158:159], v[46:47], v[218:219], v[158:159]
	v_mul_f32_e64 v165, |v165|, s19
	ds_read2_b32 v[204:205], v131 offset0:80 offset1:84
	v_exp_f32_e32 v165, v165
	ds_read2_b32 v[206:207], v131 offset0:81 offset1:85
	ds_read2_b32 v[208:209], v131 offset0:82 offset1:86
	v_add_f32_e32 v165, 1.0, v165
	ds_read2_b32 v[210:211], v131 offset0:83 offset1:87
	v_log_f32_e32 v165, v165
	ds_read2_b32 v[212:213], v131 offset0:88 offset1:92
	ds_read2_b32 v[214:215], v131 offset0:89 offset1:93
	v_fmac_f32_e32 v167, 0xbf317218, v165
	ds_read2_b32 v[216:217], v131 offset0:90 offset1:94
	v_fmamk_f32 v26, v167, 0x3d800000, v25
	ds_read2_b32 v[218:219], v131 offset0:91 offset1:95
	v_add_f32_e32 v164, v54, v156
	v_pk_mul_f32 v[160:161], v[34:35], v[174:175]
	s_waitcnt lgkmcnt(12)
	v_pk_mul_f32 v[162:163], v[42:43], v[182:183]
	v_add_f32_e32 v164, v164, v157
	v_pk_fma_f32 v[160:161], v[32:33], v[172:173], v[160:161]
	v_pk_fma_f32 v[162:163], v[40:41], v[180:181], v[162:163]
	v_add_f32_e32 v164, v164, v158
	v_pk_fma_f32 v[160:161], v[36:37], v[176:177], v[160:161]
	v_pk_fma_f32 v[162:163], v[44:45], v[184:185], v[162:163]
	v_add_f32_e32 v164, v164, v159
	v_pk_fma_f32 v[160:161], v[38:39], v[178:179], v[160:161]
	v_min_f32_e32 v166, 0, v164
	v_pk_fma_f32 v[162:163], v[46:47], v[186:187], v[162:163]
	v_mul_f32_e64 v164, |v164|, s19
	ds_read2_b32 v[172:173], v131 offset0:96 offset1:100
	v_exp_f32_e32 v164, v164
	ds_read2_b32 v[174:175], v131 offset0:97 offset1:101
	ds_read2_b32 v[176:177], v131 offset0:98 offset1:102
	v_add_f32_e32 v164, 1.0, v164
	ds_read2_b32 v[178:179], v131 offset0:99 offset1:103
	v_log_f32_e32 v164, v164
	ds_read2_b32 v[180:181], v131 offset0:104 offset1:108
	ds_read2_b32 v[182:183], v131 offset0:105 offset1:109
	v_fmac_f32_e32 v166, 0xbf317218, v164
	ds_read2_b32 v[184:185], v131 offset0:106 offset1:110
	v_fmamk_f32 v29, v166, 0x3d800000, v26
	ds_read2_b32 v[186:187], v131 offset0:107 offset1:111
	v_add_f32_e32 v165, v54, v160
	v_pk_mul_f32 v[156:157], v[34:35], v[190:191]
	s_waitcnt lgkmcnt(12)
	v_pk_mul_f32 v[158:159], v[42:43], v[198:199]
	v_add_f32_e32 v165, v165, v161
	v_pk_fma_f32 v[156:157], v[32:33], v[188:189], v[156:157]
	v_pk_fma_f32 v[158:159], v[40:41], v[196:197], v[158:159]
	v_add_f32_e32 v165, v165, v162
	v_pk_fma_f32 v[156:157], v[36:37], v[192:193], v[156:157]
	v_pk_fma_f32 v[158:159], v[44:45], v[200:201], v[158:159]
	v_add_f32_e32 v165, v165, v163
	v_pk_fma_f32 v[156:157], v[38:39], v[194:195], v[156:157]
	v_min_f32_e32 v167, 0, v165
	v_pk_fma_f32 v[158:159], v[46:47], v[202:203], v[158:159]
	v_mul_f32_e64 v165, |v165|, s19
	ds_read2_b32 v[188:189], v131 offset0:112 offset1:116
	v_exp_f32_e32 v165, v165
	ds_read2_b32 v[190:191], v131 offset0:113 offset1:117
	ds_read2_b32 v[192:193], v131 offset0:114 offset1:118
	v_add_f32_e32 v165, 1.0, v165
	ds_read2_b32 v[194:195], v131 offset0:115 offset1:119
	v_log_f32_e32 v165, v165
	ds_read2_b32 v[196:197], v131 offset0:120 offset1:124
	ds_read2_b32 v[198:199], v131 offset0:121 offset1:125
	v_fmac_f32_e32 v167, 0xbf317218, v165
	ds_read2_b32 v[200:201], v131 offset0:122 offset1:126
	v_fmamk_f32 v30, v167, 0x3d800000, v29
	ds_read2_b32 v[202:203], v131 offset0:123 offset1:127
	v_add_f32_e32 v164, v54, v156
	v_pk_mul_f32 v[160:161], v[34:35], v[206:207]
	v_add_f32_e32 v164, v164, v157
	s_waitcnt lgkmcnt(12)
	v_pk_mul_f32 v[162:163], v[42:43], v[214:215]
	v_add_f32_e32 v164, v164, v158
	v_pk_fma_f32 v[160:161], v[32:33], v[204:205], v[160:161]
	v_add_f32_e32 v164, v164, v159
	v_pk_fma_f32 v[162:163], v[40:41], v[212:213], v[162:163]
	v_min_f32_e32 v166, 0, v164
	v_pk_fma_f32 v[160:161], v[36:37], v[208:209], v[160:161]
	v_mul_f32_e64 v164, |v164|, s19
	v_pk_fma_f32 v[162:163], v[44:45], v[216:217], v[162:163]
	v_exp_f32_e32 v164, v164
	v_pk_fma_f32 v[160:161], v[38:39], v[210:211], v[160:161]
	v_pk_fma_f32 v[162:163], v[46:47], v[218:219], v[162:163]
	v_add_f32_e32 v164, 1.0, v164
	v_log_f32_e32 v164, v164
	s_nop 0
	v_fmac_f32_e32 v166, 0xbf317218, v164
	v_fmamk_f32 v31, v166, 0x3d800000, v30
	v_add_f32_e32 v165, v54, v160
	v_pk_mul_f32 v[156:157], v[34:35], v[174:175]
	v_add_f32_e32 v165, v165, v161
	s_waitcnt lgkmcnt(10)
	v_pk_mul_f32 v[158:159], v[42:43], v[182:183]
	v_add_f32_e32 v165, v165, v162
	v_pk_fma_f32 v[156:157], v[32:33], v[172:173], v[156:157]
	v_add_f32_e32 v165, v165, v163
	v_pk_fma_f32 v[158:159], v[40:41], v[180:181], v[158:159]
	v_min_f32_e32 v167, 0, v165
	v_pk_fma_f32 v[156:157], v[36:37], v[176:177], v[156:157]
	v_mul_f32_e64 v165, |v165|, s19
	s_waitcnt lgkmcnt(9)
	v_pk_fma_f32 v[158:159], v[44:45], v[184:185], v[158:159]
	v_exp_f32_e32 v165, v165
	v_pk_fma_f32 v[156:157], v[38:39], v[178:179], v[156:157]
	s_waitcnt lgkmcnt(8)
	v_pk_fma_f32 v[158:159], v[46:47], v[186:187], v[158:159]
	v_add_f32_e32 v165, 1.0, v165
	v_log_f32_e32 v165, v165
	s_nop 0
	v_fmac_f32_e32 v167, 0xbf317218, v165
	v_fmamk_f32 v76, v167, 0x3d800000, v31
	v_add_f32_e32 v164, v54, v156
	s_waitcnt lgkmcnt(6)
	v_pk_mul_f32 v[160:161], v[34:35], v[190:191]
	v_add_f32_e32 v164, v164, v157
	s_waitcnt lgkmcnt(2)
	v_pk_mul_f32 v[162:163], v[42:43], v[198:199]
	v_add_f32_e32 v164, v164, v158
	v_pk_fma_f32 v[160:161], v[32:33], v[188:189], v[160:161]
	v_add_f32_e32 v164, v164, v159
	v_pk_fma_f32 v[162:163], v[40:41], v[196:197], v[162:163]
	v_min_f32_e32 v166, 0, v164
	v_pk_fma_f32 v[160:161], v[36:37], v[192:193], v[160:161]
	v_mul_f32_e64 v164, |v164|, s19
	s_waitcnt lgkmcnt(1)
	v_pk_fma_f32 v[162:163], v[44:45], v[200:201], v[162:163]
	v_exp_f32_e32 v164, v164
	v_pk_fma_f32 v[160:161], v[38:39], v[194:195], v[160:161]
	s_waitcnt lgkmcnt(0)
	v_pk_fma_f32 v[162:163], v[46:47], v[202:203], v[162:163]
	v_add_f32_e32 v164, 1.0, v164
	v_log_f32_e32 v164, v164
	s_nop 0
	v_fmac_f32_e32 v166, 0xbf317218, v164
	v_fmamk_f32 v77, v166, 0x3d800000, v76
	v_add_f32_e32 v165, v54, v160
	v_add_f32_e32 v165, v165, v161
	v_add_f32_e32 v165, v165, v162
	v_add_f32_e32 v165, v165, v163
	v_min_f32_e32 v167, 0, v165
	v_mul_f32_e64 v165, |v165|, s19
	v_exp_f32_e32 v165, v165
	s_nop 0
	v_add_f32_e32 v165, 1.0, v165
	v_log_f32_e32 v165, v165
	s_nop 0
	v_fmac_f32_e32 v167, 0xbf317218, v165
	v_fmamk_f32 v78, v167, 0x3d800000, v77
	v_add_u32_e32 v79, s31, v62
	v_add_u32_e32 v24, s9, v69
	ds_write_b32 v60, v78
	s_waitcnt lgkmcnt(0)
	s_barrier
	ds_read_b128 v[132:135], v24
	v_add_u32_e32 v129, s8, v65
	ds_read_b128 v[136:139], v129 offset:46080
	ds_read_b128 v[140:143], v75 offset:18432
	ds_read_b128 v[144:147], v129 offset:46144
	ds_read_b128 v[148:151], v75 offset:18496
	ds_read_b128 v[152:155], v129 offset:46080
	ds_read_b128 v[156:159], v28 offset:18432
	ds_read_b128 v[160:163], v129 offset:46144
	ds_read_b128 v[164:167], v28 offset:18496
	v_add_u32_e32 v24, s8, v65
	v_add_u32_e32 v27, v70, v71
	s_mul_i32 s8, s30, 0x10200
	s_waitcnt lgkmcnt(8)
	v_pk_mul_f32 v[16:17], v[16:17], v[132:133]
	v_pk_mul_f32 v[18:19], v[18:19], v[134:135]
	v_pk_mul_f32 v[20:21], v[20:21], v[132:133]
	v_pk_mul_f32 v[22:23], v[22:23], v[134:135]
	s_waitcnt lgkmcnt(6)
	v_mfma_f32_16x16x32_bf16 v[16:19], v[136:139], v[140:143], v[16:19]
	s_nop 0
	s_nop 0
	s_waitcnt lgkmcnt(4)
	v_mfma_f32_16x16x32_bf16 v[16:19], v[144:147], v[148:151], v[16:19]
	s_nop 7
	v_cvt_pk_bf16_f32 v84, v16, v17
	v_cvt_pk_bf16_f32 v85, v18, v19
	ds_write_b64 v27, v[84:85] offset:64512
	s_nop 0
	s_nop 0
	s_waitcnt lgkmcnt(3)
	v_mfma_f32_16x16x32_bf16 v[20:23], v[152:155], v[156:159], v[20:23]
	s_nop 0
	s_nop 0
	v_add_u32_e32 v24, v70, v72
	s_waitcnt lgkmcnt(1)
	v_mfma_f32_16x16x32_bf16 v[20:23], v[160:163], v[164:167], v[20:23]
	ds_read2st64_b32 v[130:131], v61 offset1:1
	ds_read2st64_b32 v[172:173], v61 offset0:2 offset1:3
	ds_read2st64_b32 v[174:175], v61 offset0:4 offset1:5
	ds_read2st64_b32 v[176:177], v61 offset0:6 offset1:7
	ds_read_u16 v178, v79
	ds_read_u16 v179, v79 offset:9216
	ds_read_u16 v180, v79 offset:144
	ds_read_u16 v181, v79 offset:9360
	ds_read_u16 v182, v79 offset:288
	ds_read_u16 v183, v79 offset:9504
	ds_read_u16 v184, v79 offset:432
	ds_read_u16 v185, v79 offset:9648
	ds_read_u16 v186, v79 offset:576
	ds_read_u16 v187, v79 offset:9792
	ds_read_u16 v188, v79 offset:720
	ds_read_u16 v189, v79 offset:9936
	ds_read_u16 v190, v79 offset:864
	ds_read_u16 v191, v79 offset:10080
	ds_read_u16 v192, v79 offset:1008
	ds_read_u16 v193, v79 offset:10224
	s_nop 7
	v_cvt_pk_bf16_f32 v80, v20, v21
	v_cvt_pk_bf16_f32 v81, v22, v23
	ds_write_b64 v24, v[80:81] offset:64512
	s_nop 0
	s_waitcnt lgkmcnt(12)
	v_add_f32_e32 v24, 0, v130
	v_cndmask_b32_e64 v27, 0, v24, s[42:43]
	v_add_f32_e32 v28, v131, v27
	v_add_f32_e32 v24, v24, v131
	s_nop 0
	v_cndmask_b32_e64 v27, v27, v28, s[44:45]
	v_add_f32_e32 v28, v172, v27
	v_cndmask_b32_e64 v27, v27, v28, s[46:47]
	v_add_f32_e32 v24, v24, v172
	v_add_f32_e32 v28, v173, v27
	v_add_f32_e32 v24, v24, v173
	s_nop 0
	v_cndmask_b32_e64 v27, v27, v28, s[48:49]
	v_add_f32_e32 v28, v174, v27
	v_cndmask_b32_e64 v27, v27, v28, s[50:51]
	v_add_f32_e32 v24, v24, v174
	v_add_f32_e32 v28, v175, v27
	v_add_f32_e32 v24, v24, v175
	s_nop 0
	v_cndmask_b32_e64 v27, v27, v28, s[52:53]
	v_add_f32_e32 v28, v176, v27
	v_cndmask_b32_e64 v27, v27, v28, s[54:55]
	v_add_f32_e32 v28, v177, v27
	v_cndmask_b32_e64 v75, v27, v28, s[56:57]
	v_add_f32_e32 v25, v25, v75
	v_mul_f32_e32 v27, 0xbfb8aa3b, v25
	v_add_f32_e32 v24, v24, v176
	v_exp_f32_e32 v80, v27
	s_nop 0
	v_mul_f32_e32 v25, 0x3fb8aa3b, v25
	v_exp_f32_e32 v25, v25
	v_add_f32_e32 v24, v24, v177
	v_lshlrev_b32_e32 v27, 16, v178
	v_mul_f32_e32 v27, 0x3e000000, v27
	v_mul_f32_e32 v25, v27, v25
	v_cvt_pk_bf16_f32 v25, v25, s0
	ds_write_b16 v62, v25 offset:27648
	v_add_f32_e32 v25, v26, v75
	v_lshlrev_b32_e32 v82, 16, v179
	v_mul_f32_e32 v26, 0xbfb8aa3b, v25
	v_exp_f32_e32 v81, v26
	v_mul_f32_e32 v26, v80, v82
	v_cvt_pk_bf16_f32 v26, v26, s0
	ds_write_b16 v62, v26 offset:36864
	v_mul_f32_e32 v25, 0x3fb8aa3b, v25
	v_exp_f32_e32 v25, v25
	v_mul_f32_e32 v24, 0x3fb8aa3b, v24
	v_lshlrev_b32_e32 v26, 16, v180
	v_mul_f32_e32 v26, 0x3e000000, v26
	v_mul_f32_e32 v25, v26, v25
	v_exp_f32_e32 v24, v24
	v_lshlrev_b32_e32 v83, 16, v181
	v_cvt_pk_bf16_f32 v25, v25, s0
	ds_write_b16 v62, v25 offset:27792
	v_mul_f32_e32 v25, v81, v83
	v_cvt_pk_bf16_f32 v25, v25, s0
	ds_write_b16 v62, v25 offset:37008
	v_pk_mul_f32 v[26:27], v[24:25], v[80:81] op_sel_hi:[0,1]
	v_add_f32_e32 v25, v29, v75
	s_nop 0
	s_nop 0
	v_mul_f32_e32 v28, 0xbfb8aa3b, v25
	v_mul_f32_e32 v25, 0x3fb8aa3b, v25
	v_exp_f32_e32 v25, v25
	v_exp_f32_e32 v28, v28
	v_lshlrev_b32_e32 v29, 16, v182
	v_mul_f32_e32 v29, 0x3e000000, v29
	v_mul_f32_e32 v25, v25, v29
	s_waitcnt lgkmcnt(12)
	v_lshlrev_b32_e32 v80, 16, v183
	v_cvt_pk_bf16_f32 v25, v25, s0
	ds_write_b16 v62, v25 offset:27936
	v_add_f32_e32 v25, v30, v75
	v_mul_f32_e32 v30, v28, v80
	v_cvt_pk_bf16_f32 v30, v30, s0
	ds_write_b16 v62, v30 offset:37152
	v_mul_f32_e32 v29, 0xbfb8aa3b, v25
	v_mul_f32_e32 v25, 0x3fb8aa3b, v25
	v_exp_f32_e32 v25, v25
	v_exp_f32_e32 v29, v29
	v_lshlrev_b32_e32 v30, 16, v184
	v_mul_f32_e32 v30, 0x3e000000, v30
	v_mul_f32_e32 v25, v25, v30
	v_lshlrev_b32_e32 v81, 16, v185
	v_cvt_pk_bf16_f32 v25, v25, s0
	ds_write_b16 v62, v25 offset:28080
	v_mul_f32_e32 v25, v29, v81
	v_cvt_pk_bf16_f32 v25, v25, s0
	ds_write_b16 v62, v25 offset:37296
	v_pk_mul_f32 v[28:29], v[24:25], v[28:29] op_sel_hi:[0,1]
	v_add_f32_e32 v25, v31, v75
	s_nop 0
	v_mul_f32_e32 v30, 0xbfb8aa3b, v25
	v_mul_f32_e32 v25, 0x3fb8aa3b, v25
	v_pk_mul_f32 v[28:29], v[28:29], v[80:81]
	s_nop 0
	v_exp_f32_e32 v25, v25
	v_exp_f32_e32 v30, v30
	v_lshlrev_b32_e32 v31, 16, v186
	v_mul_f32_e32 v31, 0x3e000000, v31
	v_mul_f32_e32 v25, v25, v31
	s_waitcnt lgkmcnt(12)
	v_lshlrev_b32_e32 v80, 16, v187
	v_cvt_pk_bf16_f32 v25, v25, s0
	ds_write_b16 v62, v25 offset:28224
	v_add_f32_e32 v25, v76, v75
	v_mul_f32_e32 v76, v30, v80
	v_cvt_pk_bf16_f32 v76, v76, s0
	ds_write_b16 v62, v76 offset:37440
	v_mul_f32_e32 v31, 0xbfb8aa3b, v25
	v_mul_f32_e32 v25, 0x3fb8aa3b, v25
	v_exp_f32_e32 v25, v25
	v_exp_f32_e32 v31, v31
	v_lshlrev_b32_e32 v76, 16, v188
	v_mul_f32_e32 v76, 0x3e000000, v76
	v_mul_f32_e32 v25, v25, v76
	v_lshlrev_b32_e32 v81, 16, v189
	v_cvt_pk_bf16_f32 v25, v25, s0
	ds_write_b16 v62, v25 offset:28368
	v_mul_f32_e32 v25, v31, v81
	v_cvt_pk_bf16_f32 v25, v25, s0
	ds_write_b16 v62, v25 offset:37584
	v_pk_mul_f32 v[30:31], v[24:25], v[30:31] op_sel_hi:[0,1]
	v_add_f32_e32 v25, v77, v75
	s_nop 0
	v_mul_f32_e32 v76, 0xbfb8aa3b, v25
	v_mul_f32_e32 v25, 0x3fb8aa3b, v25
	v_exp_f32_e32 v25, v25
	v_pk_mul_f32 v[30:31], v[30:31], v[80:81]
	v_lshlrev_b32_e32 v77, 16, v190
	v_mul_f32_e32 v77, 0x3e000000, v77
	v_exp_f32_e32 v76, v76
	v_mul_f32_e32 v25, v25, v77
	v_cvt_pk_bf16_f32 v25, v25, s0
	ds_write_b16 v62, v25 offset:28512
	v_add_f32_e32 v25, v78, v75
	s_waitcnt lgkmcnt(12)
	v_lshlrev_b32_e32 v80, 16, v191
	v_mul_f32_e32 v75, 0xbfb8aa3b, v25
	v_exp_f32_e32 v77, v75
	v_mul_f32_e32 v75, v76, v80
	v_cvt_pk_bf16_f32 v75, v75, s0
	ds_write_b16 v62, v75 offset:37728
	v_mul_f32_e32 v25, 0x3fb8aa3b, v25
	v_exp_f32_e32 v25, v25
	v_pk_mul_f32 v[26:27], v[26:27], v[82:83]
	v_lshlrev_b32_e32 v75, 16, v192
	v_mul_f32_e32 v75, 0x3e000000, v75
	v_mul_f32_e32 v25, v25, v75
	v_lshlrev_b32_e32 v81, 16, v193
	v_cvt_pk_bf16_f32 v25, v25, s0
	ds_write_b16 v62, v25 offset:28656
	v_mul_f32_e32 v25, v77, v81
	v_cvt_pk_bf16_f32 v25, v25, s0
	v_pk_mul_f32 v[76:77], v[24:25], v[76:77] op_sel_hi:[0,1]
	v_pk_mul_f32 v[76:77], v[76:77], v[80:81]
	ds_write_b16 v62, v25 offset:37872
	v_cvt_pk_bf16_f32 v26, v26, v27
	v_cvt_pk_bf16_f32 v27, v28, v29
	v_cvt_pk_bf16_f32 v28, v30, v31
	v_cvt_pk_bf16_f32 v29, v76, v77
	v_add_u32_e32 v25, s8, v63
	ds_write_b128 v25, v[26:29] offset:46080
	s_and_saveexec_b64 s[8:9], s[58:59]
	s_cbranch_execz .LBB0_487
	s_mul_i32 s30, s30, 0xa200
	v_add_u32_e32 v25, s30, v67
	ds_write_b32 v25, v24
	s_branch .LBB0_487
